# phase-7 epilogue: serialized x-load ladder replaced by 13-deep software-pipelined loads with counted vmcnt (same arithmetic)
# speedup vs baseline: 1.0037x; 1.0004x over previous
;     __device__ __forceinline__ void operator()(const f32x4 (&acc)[2][2][4][2], const Unit& u, int wr, int wc, int fr, int fq) const {
;         constexpr int SB = SRC16 ? 2 : 4;
;         const size_t te = (size_t)u.pm * BM * ldc + (size_t)u.pn * BM;
;         char* ob = (char*)out + te * 2; const char* sb = (const char*)src + te * SB;
;         unsigned leo = (unsigned)(wr * 64 + fr) * ldc + (unsigned)(wc * 32 + 4 * fq);
;         asm volatile("" : "+v"(leo));
;         const unsigned coff = (unsigned)(u.pn * BM + wc * 32 + 4 * fq) * 4u;
;         f32x4 g4[2][2], b4[2][2];
; #pragma unroll
;         for (int bj = 0; bj < 2; ++bj)
; #pragma unroll
;             for (int n = 0; n < 2; ++n) { g4[bj][n] = *(const f32x4*)((const char*)gam + coff + (bj * HALF + n * 16) * 4) * alpha; b4[bj][n] = *(const f32x4*)((const char*)bet + coff + (bj * HALF + n * 16) * 4) * alpha; }
;         const f32x2* sp = stat + (size_t)u.pm * BM + wr * 64 + fr;
; #pragma unroll
;         for (int ai = 0; ai < 2; ++ai)
; #pragma unroll
;             for (int m = 0; m < 4; ++m) { const unsigned re = (unsigned)(ai * HALF + m * 16) * ldc + leo; const f32x2 st = sp[ai * HALF + m * 16];
; #pragma unroll
;                 for (int bj = 0; bj < 2; ++bj)
; #pragma unroll
;                     for (int n = 0; n < 2; ++n) { const unsigned ce = bj * HALF + n * 16;
;                         f32x4 v; if constexpr (SRC16) v = __builtin_convertvector(*(const h16x4*)(sb + (size_t)((re + ce) * 2u)), f32x4); else v = *(const f32x4*)(sb + (size_t)((re + ce) * 4u));
;                         *(h16x4*)(ob + (size_t)((re + ce) * 2u)) = __builtin_convertvector((v - st.x) * st.y * g4[bj][n] + b4[bj][n] + acc[ai][bj][m][n], h16x4); }
;                 asm volatile("" ::: "memory"); }
.LBB0_817:
	s_ashr_i32 s45, s44, 31
	s_ashr_i32 s47, s46, 31
	s_lshl_b64 s[18:19], s[44:45], 20
	s_lshl_b64 s[36:37], s[46:47], 8
	s_add_u32 s18, s18, s36
	s_addc_u32 s19, s19, s37
	v_lshl_add_u32 v250, s46, 10, v158
	s_lshl_b64 s[36:37], s[18:19], 1
	s_lshl_b64 s[18:19], s[18:19], 2
	s_add_u32 s46, s64, s36
	s_addc_u32 s47, s65, s37
	s_add_u32 s48, s8, s18
	s_addc_u32 s49, s9, s19
	s_lshl_b64 s[18:19], s[44:45], 11
	v_lshl_add_u64 v[134:135], v[128:129], 0, s[18:19]
	s_andn2_b64 vcc, exec, s[4:5]
	s_mov_b64 s[4:5], -1
	global_load_dwordx4 v[136:139], v250, s[10:11]
	global_load_dwordx4 v[166:169], v250, s[6:7]
	global_load_dwordx4 v[140:143], v250, s[10:11] offset:64
	global_load_dwordx4 v[170:173], v250, s[6:7] offset:64
	global_load_dwordx4 v[144:147], v250, s[10:11] offset:512
	global_load_dwordx4 v[174:177], v250, s[6:7] offset:512
	global_load_dwordx4 v[148:151], v250, s[10:11] offset:576
	global_load_dwordx4 v[178:181], v250, s[6:7] offset:576
	global_load_dwordx2 v[182:183], v[134:135], off
	global_load_dwordx2 v[184:185], v[134:135], off offset:128
	global_load_dwordx2 v[186:187], v[134:135], off offset:256
	global_load_dwordx2 v[188:189], v[134:135], off offset:384
	global_load_dwordx2 v[190:191], v[134:135], off offset:1024
	global_load_dwordx2 v[192:193], v[134:135], off offset:1152
	global_load_dwordx2 v[194:195], v[134:135], off offset:1280
	global_load_dwordx2 v[196:197], v[134:135], off offset:1408
	v_lshlrev_b32_e32 v246, 2, v159
	global_load_dwordx4 v[198:201], v246, s[48:49]
	global_load_dwordx4 v[202:205], v246, s[48:49] offset:64
	global_load_dwordx4 v[206:209], v246, s[48:49] offset:512
	global_load_dwordx4 v[210:213], v246, s[48:49] offset:576
	v_add_u32_e32 v246, 0x10000, v159
	v_lshlrev_b32_e32 v246, 2, v246
	global_load_dwordx4 v[214:217], v246, s[48:49]
	global_load_dwordx4 v[218:221], v246, s[48:49] offset:64
	global_load_dwordx4 v[222:225], v246, s[48:49] offset:512
	global_load_dwordx4 v[226:229], v246, s[48:49] offset:576
	v_add_u32_e32 v246, 0x20000, v159
	v_lshlrev_b32_e32 v246, 2, v246
	global_load_dwordx4 v[230:233], v246, s[48:49]
	global_load_dwordx4 v[234:237], v246, s[48:49] offset:64
	global_load_dwordx4 v[238:241], v246, s[48:49] offset:512
	global_load_dwordx4 v[242:245], v246, s[48:49] offset:576
	v_add_u32_e32 v246, 0x30000, v159
	v_lshlrev_b32_e32 v246, 2, v246
	global_load_dwordx4 v[152:155], v246, s[48:49]
	s_waitcnt vmcnt(21)
	v_pk_mul_f32 v[136:137], v[136:137], s[16:17] op_sel_hi:[1,0]
	v_pk_mul_f32 v[166:167], v[166:167], s[16:17] op_sel_hi:[1,0]
	v_pk_mul_f32 v[138:139], v[138:139], s[16:17] op_sel_hi:[1,0]
	v_pk_mul_f32 v[168:169], v[168:169], s[16:17] op_sel_hi:[1,0]
	v_pk_mul_f32 v[140:141], v[140:141], s[16:17] op_sel_hi:[1,0]
	v_pk_mul_f32 v[170:171], v[170:171], s[16:17] op_sel_hi:[1,0]
	v_pk_mul_f32 v[142:143], v[142:143], s[16:17] op_sel_hi:[1,0]
	v_pk_mul_f32 v[172:173], v[172:173], s[16:17] op_sel_hi:[1,0]
	v_pk_mul_f32 v[144:145], v[144:145], s[16:17] op_sel_hi:[1,0]
	v_pk_mul_f32 v[174:175], v[174:175], s[16:17] op_sel_hi:[1,0]
	v_pk_mul_f32 v[146:147], v[146:147], s[16:17] op_sel_hi:[1,0]
	v_pk_mul_f32 v[176:177], v[176:177], s[16:17] op_sel_hi:[1,0]
	v_pk_mul_f32 v[148:149], v[148:149], s[16:17] op_sel_hi:[1,0]
	v_pk_mul_f32 v[178:179], v[178:179], s[16:17] op_sel_hi:[1,0]
	v_pk_mul_f32 v[150:151], v[150:151], s[16:17] op_sel_hi:[1,0]
	v_pk_mul_f32 v[180:181], v[180:181], s[16:17] op_sel_hi:[1,0]
	s_waitcnt vmcnt(12)
	v_sub_f32_e32 v201, v201, v182
	v_sub_f32_e32 v200, v200, v182
	v_sub_f32_e32 v199, v199, v182
	v_sub_f32_e32 v198, v198, v182
	v_pk_mul_f32 v[198:199], v[182:183], v[198:199] op_sel:[1,0]
	v_pk_mul_f32 v[200:201], v[182:183], v[200:201] op_sel:[1,0]
	v_pk_fma_f32 v[198:199], v[136:137], v[198:199], v[166:167]
	v_pk_fma_f32 v[200:201], v[138:139], v[200:201], v[168:169]
	v_pk_add_f32 v[124:125], v[124:125], v[198:199]
	v_pk_add_f32 v[126:127], v[126:127], v[200:201]
	v_lshlrev_b32_e32 v247, 1, v159
	s_nop 0
	v_cvt_pk_f16_f32 v127, v126, v127
	v_cvt_pk_f16_f32 v126, v124, v125
	global_store_dwordx2 v247, v[126:127], s[46:47]
	global_load_dwordx4 v[198:201], v246, s[48:49] offset:64
	s_waitcnt vmcnt(13)
	v_sub_f32_e32 v205, v205, v182
	v_sub_f32_e32 v204, v204, v182
	v_sub_f32_e32 v203, v203, v182
	v_sub_f32_e32 v202, v202, v182
	v_pk_mul_f32 v[202:203], v[182:183], v[202:203] op_sel:[1,0]
	v_pk_mul_f32 v[204:205], v[182:183], v[204:205] op_sel:[1,0]
	v_pk_fma_f32 v[202:203], v[140:141], v[202:203], v[170:171]
	v_pk_fma_f32 v[204:205], v[142:143], v[204:205], v[172:173]
	v_pk_add_f32 v[120:121], v[120:121], v[202:203]
	v_pk_add_f32 v[122:123], v[122:123], v[204:205]
	s_nop 0
	v_cvt_pk_f16_f32 v123, v122, v123
	v_cvt_pk_f16_f32 v122, v120, v121
	global_store_dwordx2 v247, v[122:123], s[46:47] offset:32
	global_load_dwordx4 v[202:205], v246, s[48:49] offset:512
	s_waitcnt vmcnt(14)
	v_sub_f32_e32 v209, v209, v182
	v_sub_f32_e32 v208, v208, v182
	v_sub_f32_e32 v207, v207, v182
	v_sub_f32_e32 v206, v206, v182
	v_pk_mul_f32 v[206:207], v[182:183], v[206:207] op_sel:[1,0]
	v_pk_mul_f32 v[208:209], v[182:183], v[208:209] op_sel:[1,0]
	v_pk_fma_f32 v[206:207], v[144:145], v[206:207], v[174:175]
	v_pk_fma_f32 v[208:209], v[146:147], v[208:209], v[176:177]
	v_pk_add_f32 v[116:117], v[116:117], v[206:207]
	v_pk_add_f32 v[118:119], v[118:119], v[208:209]
	s_nop 0
	v_cvt_pk_f16_f32 v119, v118, v119
	v_cvt_pk_f16_f32 v118, v116, v117
	global_store_dwordx2 v247, v[118:119], s[46:47] offset:256
	global_load_dwordx4 v[206:209], v246, s[48:49] offset:576
	s_waitcnt vmcnt(15)
;     __device__ __forceinline__ void operator()(const f32x4 (&acc)[2][2][4][2], const Unit& u, int wr, int wc, int fr, int fq) const {
;     ...
;         for (int ai = 0; ai < 2; ++ai)
; #pragma unroll
;             for (int m = 0; m < 4; ++m) { const unsigned re = (unsigned)(ai * HALF + m * 16) * ldc + leo; const f32x2 st = sp[ai * HALF + m * 16];
; #pragma unroll
;                 for (int bj = 0; bj < 2; ++bj)
; #pragma unroll
;                     for (int n = 0; n < 2; ++n) { const unsigned ce = bj * HALF + n * 16;
;                         f32x4 v; if constexpr (SRC16) v = __builtin_convertvector(*(const h16x4*)(sb + (size_t)((re + ce) * 2u)), f32x4); else v = *(const f32x4*)(sb + (size_t)((re + ce) * 4u));
;                         *(h16x4*)(ob + (size_t)((re + ce) * 2u)) = __builtin_convertvector((v - st.x) * st.y * g4[bj][n] + b4[bj][n] + acc[ai][bj][m][n], h16x4); }
;                 asm volatile("" ::: "memory"); }
	v_sub_f32_e32 v213, v213, v182
	v_sub_f32_e32 v212, v212, v182
	v_sub_f32_e32 v211, v211, v182
	v_sub_f32_e32 v210, v210, v182
	v_pk_mul_f32 v[210:211], v[182:183], v[210:211] op_sel:[1,0]
	v_pk_mul_f32 v[212:213], v[182:183], v[212:213] op_sel:[1,0]
	v_pk_fma_f32 v[210:211], v[148:149], v[210:211], v[178:179]
	v_pk_fma_f32 v[212:213], v[150:151], v[212:213], v[180:181]
	v_pk_add_f32 v[112:113], v[112:113], v[210:211]
	v_pk_add_f32 v[114:115], v[114:115], v[212:213]
	s_nop 0
	v_cvt_pk_f16_f32 v115, v114, v115
	v_cvt_pk_f16_f32 v114, v112, v113
	global_store_dwordx2 v247, v[114:115], s[46:47] offset:288
	v_add_u32_e32 v246, 0x80000, v159
	v_lshlrev_b32_e32 v246, 2, v246
	global_load_dwordx4 v[210:213], v246, s[48:49]
	s_waitcnt vmcnt(16)
	v_sub_f32_e32 v217, v217, v184
	v_sub_f32_e32 v216, v216, v184
	v_sub_f32_e32 v215, v215, v184
	v_sub_f32_e32 v214, v214, v184
	v_pk_mul_f32 v[214:215], v[184:185], v[214:215] op_sel:[1,0]
	v_pk_mul_f32 v[216:217], v[184:185], v[216:217] op_sel:[1,0]
	v_pk_fma_f32 v[214:215], v[136:137], v[214:215], v[166:167]
	v_pk_fma_f32 v[216:217], v[138:139], v[216:217], v[168:169]
	v_pk_add_f32 v[108:109], v[108:109], v[214:215]
	v_pk_add_f32 v[110:111], v[110:111], v[216:217]
	v_add_u32_e32 v247, 0x10000, v159
	v_lshlrev_b32_e32 v247, 1, v247
	v_cvt_pk_f16_f32 v111, v110, v111
	v_cvt_pk_f16_f32 v110, v108, v109
	global_store_dwordx2 v247, v[110:111], s[46:47]
	global_load_dwordx4 v[214:217], v246, s[48:49] offset:64
	s_waitcnt vmcnt(17)
	v_sub_f32_e32 v221, v221, v184
	v_sub_f32_e32 v220, v220, v184
	v_sub_f32_e32 v219, v219, v184
	v_sub_f32_e32 v218, v218, v184
	v_pk_mul_f32 v[218:219], v[184:185], v[218:219] op_sel:[1,0]
	v_pk_mul_f32 v[220:221], v[184:185], v[220:221] op_sel:[1,0]
	v_pk_fma_f32 v[218:219], v[140:141], v[218:219], v[170:171]
	v_pk_fma_f32 v[220:221], v[142:143], v[220:221], v[172:173]
	v_pk_add_f32 v[104:105], v[104:105], v[218:219]
	v_pk_add_f32 v[106:107], v[106:107], v[220:221]
	s_nop 0
	v_cvt_pk_f16_f32 v107, v106, v107
	v_cvt_pk_f16_f32 v106, v104, v105
	global_store_dwordx2 v247, v[106:107], s[46:47] offset:32
	global_load_dwordx4 v[218:221], v246, s[48:49] offset:512
	s_waitcnt vmcnt(18)
	v_sub_f32_e32 v225, v225, v184
	v_sub_f32_e32 v224, v224, v184
	v_sub_f32_e32 v223, v223, v184
	v_sub_f32_e32 v222, v222, v184
	v_pk_mul_f32 v[222:223], v[184:185], v[222:223] op_sel:[1,0]
	v_pk_mul_f32 v[224:225], v[184:185], v[224:225] op_sel:[1,0]
	v_pk_fma_f32 v[222:223], v[144:145], v[222:223], v[174:175]
	v_pk_fma_f32 v[224:225], v[146:147], v[224:225], v[176:177]
	v_pk_add_f32 v[100:101], v[100:101], v[222:223]
	v_pk_add_f32 v[102:103], v[102:103], v[224:225]
	s_nop 0
	v_cvt_pk_f16_f32 v103, v102, v103
	v_cvt_pk_f16_f32 v102, v100, v101
	global_store_dwordx2 v247, v[102:103], s[46:47] offset:256
	global_load_dwordx4 v[222:225], v246, s[48:49] offset:576
	s_waitcnt vmcnt(19)
	v_sub_f32_e32 v229, v229, v184
	v_sub_f32_e32 v228, v228, v184
	v_sub_f32_e32 v227, v227, v184
	v_sub_f32_e32 v226, v226, v184
	v_pk_mul_f32 v[226:227], v[184:185], v[226:227] op_sel:[1,0]
	v_pk_mul_f32 v[228:229], v[184:185], v[228:229] op_sel:[1,0]
	v_pk_fma_f32 v[226:227], v[148:149], v[226:227], v[178:179]
	v_pk_fma_f32 v[228:229], v[150:151], v[228:229], v[180:181]
	v_pk_add_f32 v[96:97], v[96:97], v[226:227]
	v_pk_add_f32 v[98:99], v[98:99], v[228:229]
	s_nop 0
	v_cvt_pk_f16_f32 v99, v98, v99
	v_cvt_pk_f16_f32 v98, v96, v97
	global_store_dwordx2 v247, v[98:99], s[46:47] offset:288
	v_add_u32_e32 v246, 0x90000, v159
	v_lshlrev_b32_e32 v246, 2, v246
	global_load_dwordx4 v[226:229], v246, s[48:49]
	s_waitcnt vmcnt(20)
	v_sub_f32_e32 v233, v233, v186
	v_sub_f32_e32 v232, v232, v186
	v_sub_f32_e32 v231, v231, v186
	v_sub_f32_e32 v230, v230, v186
	v_pk_mul_f32 v[230:231], v[186:187], v[230:231] op_sel:[1,0]
	v_pk_mul_f32 v[232:233], v[186:187], v[232:233] op_sel:[1,0]
	v_pk_fma_f32 v[230:231], v[136:137], v[230:231], v[166:167]
	v_pk_fma_f32 v[232:233], v[138:139], v[232:233], v[168:169]
	v_pk_add_f32 v[92:93], v[92:93], v[230:231]
	v_pk_add_f32 v[94:95], v[94:95], v[232:233]
	v_add_u32_e32 v247, 0x20000, v159
	v_lshlrev_b32_e32 v247, 1, v247
	v_cvt_pk_f16_f32 v95, v94, v95
	v_cvt_pk_f16_f32 v94, v92, v93
	global_store_dwordx2 v247, v[94:95], s[46:47]
	global_load_dwordx4 v[230:233], v246, s[48:49] offset:64
	s_waitcnt vmcnt(21)
	v_sub_f32_e32 v237, v237, v186
	v_sub_f32_e32 v236, v236, v186
	v_sub_f32_e32 v235, v235, v186
	v_sub_f32_e32 v234, v234, v186
	v_pk_mul_f32 v[234:235], v[186:187], v[234:235] op_sel:[1,0]
	v_pk_mul_f32 v[236:237], v[186:187], v[236:237] op_sel:[1,0]
	v_pk_fma_f32 v[234:235], v[140:141], v[234:235], v[170:171]
	v_pk_fma_f32 v[236:237], v[142:143], v[236:237], v[172:173]
	v_pk_add_f32 v[88:89], v[88:89], v[234:235]
	v_pk_add_f32 v[90:91], v[90:91], v[236:237]
	s_nop 0
	v_cvt_pk_f16_f32 v91, v90, v91
	v_cvt_pk_f16_f32 v90, v88, v89
	global_store_dwordx2 v247, v[90:91], s[46:47] offset:32
	global_load_dwordx4 v[234:237], v246, s[48:49] offset:512
	s_waitcnt vmcnt(22)
	v_sub_f32_e32 v241, v241, v186
	v_sub_f32_e32 v240, v240, v186
	v_sub_f32_e32 v239, v239, v186
	v_sub_f32_e32 v238, v238, v186
	v_pk_mul_f32 v[238:239], v[186:187], v[238:239] op_sel:[1,0]
	v_pk_mul_f32 v[240:241], v[186:187], v[240:241] op_sel:[1,0]
	v_pk_fma_f32 v[238:239], v[144:145], v[238:239], v[174:175]
	v_pk_fma_f32 v[240:241], v[146:147], v[240:241], v[176:177]
	v_pk_add_f32 v[84:85], v[84:85], v[238:239]
	v_pk_add_f32 v[86:87], v[86:87], v[240:241]
	s_nop 0
	v_cvt_pk_f16_f32 v87, v86, v87
	v_cvt_pk_f16_f32 v86, v84, v85
	global_store_dwordx2 v247, v[86:87], s[46:47] offset:256
	global_load_dwordx4 v[238:241], v246, s[48:49] offset:576
	s_waitcnt vmcnt(23)
;     __device__ __forceinline__ void operator()(const f32x4 (&acc)[2][2][4][2], const Unit& u, int wr, int wc, int fr, int fq) const {
;     ...
;         for (int ai = 0; ai < 2; ++ai)
; #pragma unroll
;             for (int m = 0; m < 4; ++m) { const unsigned re = (unsigned)(ai * HALF + m * 16) * ldc + leo; const f32x2 st = sp[ai * HALF + m * 16];
; #pragma unroll
;                 for (int bj = 0; bj < 2; ++bj)
; #pragma unroll
;                     for (int n = 0; n < 2; ++n) { const unsigned ce = bj * HALF + n * 16;
;                         f32x4 v; if constexpr (SRC16) v = __builtin_convertvector(*(const h16x4*)(sb + (size_t)((re + ce) * 2u)), f32x4); else v = *(const f32x4*)(sb + (size_t)((re + ce) * 4u));
;                         *(h16x4*)(ob + (size_t)((re + ce) * 2u)) = __builtin_convertvector((v - st.x) * st.y * g4[bj][n] + b4[bj][n] + acc[ai][bj][m][n], h16x4); }
;                 asm volatile("" ::: "memory"); }
	v_sub_f32_e32 v245, v245, v186
	v_sub_f32_e32 v244, v244, v186
	v_sub_f32_e32 v243, v243, v186
	v_sub_f32_e32 v242, v242, v186
	v_pk_mul_f32 v[242:243], v[186:187], v[242:243] op_sel:[1,0]
	v_pk_mul_f32 v[244:245], v[186:187], v[244:245] op_sel:[1,0]
	v_pk_fma_f32 v[242:243], v[148:149], v[242:243], v[178:179]
	v_pk_fma_f32 v[244:245], v[150:151], v[244:245], v[180:181]
	v_pk_add_f32 v[80:81], v[80:81], v[242:243]
	v_pk_add_f32 v[82:83], v[82:83], v[244:245]
	s_nop 0
	v_cvt_pk_f16_f32 v83, v82, v83
	v_cvt_pk_f16_f32 v82, v80, v81
	global_store_dwordx2 v247, v[82:83], s[46:47] offset:288
	v_add_u32_e32 v246, 0xa0000, v159
	v_lshlrev_b32_e32 v246, 2, v246
	global_load_dwordx4 v[242:245], v246, s[48:49]
	s_waitcnt vmcnt(24)
	v_sub_f32_e32 v155, v155, v188
	v_sub_f32_e32 v154, v154, v188
	v_sub_f32_e32 v153, v153, v188
	v_sub_f32_e32 v152, v152, v188
	v_pk_mul_f32 v[152:153], v[188:189], v[152:153] op_sel:[1,0]
	v_pk_mul_f32 v[154:155], v[188:189], v[154:155] op_sel:[1,0]
	v_pk_fma_f32 v[152:153], v[136:137], v[152:153], v[166:167]
	v_pk_fma_f32 v[154:155], v[138:139], v[154:155], v[168:169]
	v_pk_add_f32 v[76:77], v[76:77], v[152:153]
	v_pk_add_f32 v[78:79], v[78:79], v[154:155]
	v_add_u32_e32 v247, 0x30000, v159
	v_lshlrev_b32_e32 v247, 1, v247
	v_cvt_pk_f16_f32 v79, v78, v79
	v_cvt_pk_f16_f32 v78, v76, v77
	global_store_dwordx2 v247, v[78:79], s[46:47]
	global_load_dwordx4 v[152:155], v246, s[48:49] offset:64
	s_waitcnt vmcnt(24)
	v_sub_f32_e32 v201, v201, v188
	v_sub_f32_e32 v200, v200, v188
	v_sub_f32_e32 v199, v199, v188
	v_sub_f32_e32 v198, v198, v188
	v_pk_mul_f32 v[198:199], v[188:189], v[198:199] op_sel:[1,0]
	v_pk_mul_f32 v[200:201], v[188:189], v[200:201] op_sel:[1,0]
	v_pk_fma_f32 v[198:199], v[140:141], v[198:199], v[170:171]
	v_pk_fma_f32 v[200:201], v[142:143], v[200:201], v[172:173]
	v_pk_add_f32 v[72:73], v[72:73], v[198:199]
	v_pk_add_f32 v[74:75], v[74:75], v[200:201]
	s_nop 0
	v_cvt_pk_f16_f32 v75, v74, v75
	v_cvt_pk_f16_f32 v74, v72, v73
	global_store_dwordx2 v247, v[74:75], s[46:47] offset:32
	global_load_dwordx4 v[198:201], v246, s[48:49] offset:512
	s_waitcnt vmcnt(24)
	v_sub_f32_e32 v205, v205, v188
	v_sub_f32_e32 v204, v204, v188
	v_sub_f32_e32 v203, v203, v188
	v_sub_f32_e32 v202, v202, v188
	v_pk_mul_f32 v[202:203], v[188:189], v[202:203] op_sel:[1,0]
	v_pk_mul_f32 v[204:205], v[188:189], v[204:205] op_sel:[1,0]
	v_pk_fma_f32 v[202:203], v[144:145], v[202:203], v[174:175]
	v_pk_fma_f32 v[204:205], v[146:147], v[204:205], v[176:177]
	v_pk_add_f32 v[68:69], v[68:69], v[202:203]
	v_pk_add_f32 v[70:71], v[70:71], v[204:205]
	s_nop 0
	v_cvt_pk_f16_f32 v71, v70, v71
	v_cvt_pk_f16_f32 v70, v68, v69
	global_store_dwordx2 v247, v[70:71], s[46:47] offset:256
	global_load_dwordx4 v[202:205], v246, s[48:49] offset:576
	s_waitcnt vmcnt(24)
	v_sub_f32_e32 v209, v209, v188
	v_sub_f32_e32 v208, v208, v188
	v_sub_f32_e32 v207, v207, v188
	v_sub_f32_e32 v206, v206, v188
	v_pk_mul_f32 v[206:207], v[188:189], v[206:207] op_sel:[1,0]
	v_pk_mul_f32 v[208:209], v[188:189], v[208:209] op_sel:[1,0]
	v_pk_fma_f32 v[206:207], v[148:149], v[206:207], v[178:179]
	v_pk_fma_f32 v[208:209], v[150:151], v[208:209], v[180:181]
	v_pk_add_f32 v[64:65], v[64:65], v[206:207]
	v_pk_add_f32 v[66:67], v[66:67], v[208:209]
	s_nop 0
	v_cvt_pk_f16_f32 v67, v66, v67
	v_cvt_pk_f16_f32 v66, v64, v65
	global_store_dwordx2 v247, v[66:67], s[46:47] offset:288
	v_add_u32_e32 v246, 0xb0000, v159
	v_lshlrev_b32_e32 v246, 2, v246
	global_load_dwordx4 v[206:209], v246, s[48:49]
	s_waitcnt vmcnt(24)
	v_sub_f32_e32 v213, v213, v190
	v_sub_f32_e32 v212, v212, v190
	v_sub_f32_e32 v211, v211, v190
	v_sub_f32_e32 v210, v210, v190
	v_pk_mul_f32 v[210:211], v[190:191], v[210:211] op_sel:[1,0]
	v_pk_mul_f32 v[212:213], v[190:191], v[212:213] op_sel:[1,0]
	v_pk_fma_f32 v[210:211], v[136:137], v[210:211], v[166:167]
	v_pk_fma_f32 v[212:213], v[138:139], v[212:213], v[168:169]
	v_pk_add_f32 v[60:61], v[60:61], v[210:211]
	v_pk_add_f32 v[62:63], v[62:63], v[212:213]
	v_add_u32_e32 v247, 0x80000, v159
	v_lshlrev_b32_e32 v247, 1, v247
	v_cvt_pk_f16_f32 v63, v62, v63
	v_cvt_pk_f16_f32 v62, v60, v61
	global_store_dwordx2 v247, v[62:63], s[46:47]
	global_load_dwordx4 v[210:213], v246, s[48:49] offset:64
	s_waitcnt vmcnt(24)
	v_sub_f32_e32 v217, v217, v190
	v_sub_f32_e32 v216, v216, v190
	v_sub_f32_e32 v215, v215, v190
	v_sub_f32_e32 v214, v214, v190
	v_pk_mul_f32 v[214:215], v[190:191], v[214:215] op_sel:[1,0]
	v_pk_mul_f32 v[216:217], v[190:191], v[216:217] op_sel:[1,0]
	v_pk_fma_f32 v[214:215], v[140:141], v[214:215], v[170:171]
	v_pk_fma_f32 v[216:217], v[142:143], v[216:217], v[172:173]
	v_pk_add_f32 v[56:57], v[56:57], v[214:215]
	v_pk_add_f32 v[58:59], v[58:59], v[216:217]
	s_nop 0
	v_cvt_pk_f16_f32 v59, v58, v59
	v_cvt_pk_f16_f32 v58, v56, v57
	global_store_dwordx2 v247, v[58:59], s[46:47] offset:32
	global_load_dwordx4 v[214:217], v246, s[48:49] offset:512
	s_waitcnt vmcnt(24)
	v_sub_f32_e32 v221, v221, v190
	v_sub_f32_e32 v220, v220, v190
	v_sub_f32_e32 v219, v219, v190
	v_sub_f32_e32 v218, v218, v190
	v_pk_mul_f32 v[218:219], v[190:191], v[218:219] op_sel:[1,0]
	v_pk_mul_f32 v[220:221], v[190:191], v[220:221] op_sel:[1,0]
	v_pk_fma_f32 v[218:219], v[144:145], v[218:219], v[174:175]
	v_pk_fma_f32 v[220:221], v[146:147], v[220:221], v[176:177]
	v_pk_add_f32 v[52:53], v[52:53], v[218:219]
	v_pk_add_f32 v[54:55], v[54:55], v[220:221]
	s_nop 0
	v_cvt_pk_f16_f32 v55, v54, v55
	v_cvt_pk_f16_f32 v54, v52, v53
	global_store_dwordx2 v247, v[54:55], s[46:47] offset:256
	global_load_dwordx4 v[218:221], v246, s[48:49] offset:576
	s_waitcnt vmcnt(24)
;     __device__ __forceinline__ void operator()(const f32x4 (&acc)[2][2][4][2], const Unit& u, int wr, int wc, int fr, int fq) const {
;     ...
;         for (int ai = 0; ai < 2; ++ai)
; #pragma unroll
;             for (int m = 0; m < 4; ++m) { const unsigned re = (unsigned)(ai * HALF + m * 16) * ldc + leo; const f32x2 st = sp[ai * HALF + m * 16];
; #pragma unroll
;                 for (int bj = 0; bj < 2; ++bj)
; #pragma unroll
;                     for (int n = 0; n < 2; ++n) { const unsigned ce = bj * HALF + n * 16;
;                         f32x4 v; if constexpr (SRC16) v = __builtin_convertvector(*(const h16x4*)(sb + (size_t)((re + ce) * 2u)), f32x4); else v = *(const f32x4*)(sb + (size_t)((re + ce) * 4u));
;                         *(h16x4*)(ob + (size_t)((re + ce) * 2u)) = __builtin_convertvector((v - st.x) * st.y * g4[bj][n] + b4[bj][n] + acc[ai][bj][m][n], h16x4); }
;                 asm volatile("" ::: "memory"); }
	v_sub_f32_e32 v225, v225, v190
	v_sub_f32_e32 v224, v224, v190
	v_sub_f32_e32 v223, v223, v190
	v_sub_f32_e32 v222, v222, v190
	v_pk_mul_f32 v[222:223], v[190:191], v[222:223] op_sel:[1,0]
	v_pk_mul_f32 v[224:225], v[190:191], v[224:225] op_sel:[1,0]
	v_pk_fma_f32 v[222:223], v[148:149], v[222:223], v[178:179]
	v_pk_fma_f32 v[224:225], v[150:151], v[224:225], v[180:181]
	v_pk_add_f32 v[48:49], v[48:49], v[222:223]
	v_pk_add_f32 v[50:51], v[50:51], v[224:225]
	s_nop 0
	v_cvt_pk_f16_f32 v51, v50, v51
	v_cvt_pk_f16_f32 v50, v48, v49
	global_store_dwordx2 v247, v[50:51], s[46:47] offset:288
	s_waitcnt vmcnt(23)
	v_sub_f32_e32 v229, v229, v192
	v_sub_f32_e32 v228, v228, v192
	v_sub_f32_e32 v227, v227, v192
	v_sub_f32_e32 v226, v226, v192
	v_pk_mul_f32 v[226:227], v[192:193], v[226:227] op_sel:[1,0]
	v_pk_mul_f32 v[228:229], v[192:193], v[228:229] op_sel:[1,0]
	v_pk_fma_f32 v[226:227], v[136:137], v[226:227], v[166:167]
	v_pk_fma_f32 v[228:229], v[138:139], v[228:229], v[168:169]
	v_pk_add_f32 v[44:45], v[44:45], v[226:227]
	v_pk_add_f32 v[46:47], v[46:47], v[228:229]
	v_add_u32_e32 v247, 0x90000, v159
	v_lshlrev_b32_e32 v247, 1, v247
	v_cvt_pk_f16_f32 v47, v46, v47
	v_cvt_pk_f16_f32 v46, v44, v45
	global_store_dwordx2 v247, v[46:47], s[46:47]
	s_waitcnt vmcnt(22)
	v_sub_f32_e32 v233, v233, v192
	v_sub_f32_e32 v232, v232, v192
	v_sub_f32_e32 v231, v231, v192
	v_sub_f32_e32 v230, v230, v192
	v_pk_mul_f32 v[230:231], v[192:193], v[230:231] op_sel:[1,0]
	v_pk_mul_f32 v[232:233], v[192:193], v[232:233] op_sel:[1,0]
	v_pk_fma_f32 v[230:231], v[140:141], v[230:231], v[170:171]
	v_pk_fma_f32 v[232:233], v[142:143], v[232:233], v[172:173]
	v_pk_add_f32 v[40:41], v[40:41], v[230:231]
	v_pk_add_f32 v[42:43], v[42:43], v[232:233]
	s_nop 0
	v_cvt_pk_f16_f32 v43, v42, v43
	v_cvt_pk_f16_f32 v42, v40, v41
	global_store_dwordx2 v247, v[42:43], s[46:47] offset:32
	s_waitcnt vmcnt(21)
	v_sub_f32_e32 v237, v237, v192
	v_sub_f32_e32 v236, v236, v192
	v_sub_f32_e32 v235, v235, v192
	v_sub_f32_e32 v234, v234, v192
	v_pk_mul_f32 v[234:235], v[192:193], v[234:235] op_sel:[1,0]
	v_pk_mul_f32 v[236:237], v[192:193], v[236:237] op_sel:[1,0]
	v_pk_fma_f32 v[234:235], v[144:145], v[234:235], v[174:175]
	v_pk_fma_f32 v[236:237], v[146:147], v[236:237], v[176:177]
	v_pk_add_f32 v[36:37], v[36:37], v[234:235]
	v_pk_add_f32 v[38:39], v[38:39], v[236:237]
	s_nop 0
	v_cvt_pk_f16_f32 v39, v38, v39
	v_cvt_pk_f16_f32 v38, v36, v37
	global_store_dwordx2 v247, v[38:39], s[46:47] offset:256
	s_waitcnt vmcnt(20)
	v_sub_f32_e32 v241, v241, v192
	v_sub_f32_e32 v240, v240, v192
	v_sub_f32_e32 v239, v239, v192
	v_sub_f32_e32 v238, v238, v192
	v_pk_mul_f32 v[238:239], v[192:193], v[238:239] op_sel:[1,0]
	v_pk_mul_f32 v[240:241], v[192:193], v[240:241] op_sel:[1,0]
	v_pk_fma_f32 v[238:239], v[148:149], v[238:239], v[178:179]
	v_pk_fma_f32 v[240:241], v[150:151], v[240:241], v[180:181]
	v_pk_add_f32 v[32:33], v[32:33], v[238:239]
	v_pk_add_f32 v[34:35], v[34:35], v[240:241]
	s_nop 0
	v_cvt_pk_f16_f32 v35, v34, v35
	v_cvt_pk_f16_f32 v34, v32, v33
	global_store_dwordx2 v247, v[34:35], s[46:47] offset:288
	s_waitcnt vmcnt(19)
	v_sub_f32_e32 v245, v245, v194
	v_sub_f32_e32 v244, v244, v194
	v_sub_f32_e32 v243, v243, v194
	v_sub_f32_e32 v242, v242, v194
	v_pk_mul_f32 v[242:243], v[194:195], v[242:243] op_sel:[1,0]
	v_pk_mul_f32 v[244:245], v[194:195], v[244:245] op_sel:[1,0]
	v_pk_fma_f32 v[242:243], v[136:137], v[242:243], v[166:167]
	v_pk_fma_f32 v[244:245], v[138:139], v[244:245], v[168:169]
	v_pk_add_f32 v[28:29], v[28:29], v[242:243]
	v_pk_add_f32 v[30:31], v[30:31], v[244:245]
	v_add_u32_e32 v247, 0xa0000, v159
	v_lshlrev_b32_e32 v247, 1, v247
	v_cvt_pk_f16_f32 v31, v30, v31
	v_cvt_pk_f16_f32 v30, v28, v29
	global_store_dwordx2 v247, v[30:31], s[46:47]
	s_waitcnt vmcnt(18)
	v_sub_f32_e32 v155, v155, v194
	v_sub_f32_e32 v154, v154, v194
	v_sub_f32_e32 v153, v153, v194
	v_sub_f32_e32 v152, v152, v194
	v_pk_mul_f32 v[152:153], v[194:195], v[152:153] op_sel:[1,0]
	v_pk_mul_f32 v[154:155], v[194:195], v[154:155] op_sel:[1,0]
	v_pk_fma_f32 v[152:153], v[140:141], v[152:153], v[170:171]
	v_pk_fma_f32 v[154:155], v[142:143], v[154:155], v[172:173]
	v_pk_add_f32 v[24:25], v[24:25], v[152:153]
	v_pk_add_f32 v[26:27], v[26:27], v[154:155]
	s_nop 0
	v_cvt_pk_f16_f32 v27, v26, v27
	v_cvt_pk_f16_f32 v26, v24, v25
	global_store_dwordx2 v247, v[26:27], s[46:47] offset:32
	s_waitcnt vmcnt(17)
; #define PG8_BAR __builtin_amdgcn_s_barrier()
;     __device__ __forceinline__ void operator()(const f32x4 (&acc)[2][2][4][2], const Unit& u, int wr, int wc, int fr, int fq) const {
;     ...
;         for (int ai = 0; ai < 2; ++ai)
; #pragma unroll
;             for (int m = 0; m < 4; ++m) { const unsigned re = (unsigned)(ai * HALF + m * 16) * ldc + leo; const f32x2 st = sp[ai * HALF + m * 16];
; #pragma unroll
;                 for (int bj = 0; bj < 2; ++bj)
; #pragma unroll
;                     for (int n = 0; n < 2; ++n) { const unsigned ce = bj * HALF + n * 16;
;                         f32x4 v; if constexpr (SRC16) v = __builtin_convertvector(*(const h16x4*)(sb + (size_t)((re + ce) * 2u)), f32x4); else v = *(const f32x4*)(sb + (size_t)((re + ce) * 4u));
;                         *(h16x4*)(ob + (size_t)((re + ce) * 2u)) = __builtin_convertvector((v - st.x) * st.y * g4[bj][n] + b4[bj][n] + acc[ai][bj][m][n], h16x4); }
;                 asm volatile("" ::: "memory"); }
; template <class Epi, class Addr, bool ALIGN_EPI = true, class Order = StaticOrder>
; __device__ __forceinline__ void gemm_phase(LAS unsigned char* lds, const Gemm g, const Order& S, const Epi& E, const int wid) {
;     ...
;         if constexpr (ALIGN_EPI) { if (wr == 0) PG8_BAR; }
;         E(acc, cur, wr, wc, fr, fq);
;         if (!has_next) break;
; #pragma unroll
;         for (int a = 0; a < 2; ++a)
; #pragma unroll
;             for (int b = 0; b < 2; ++b)
; #pragma unroll
;                 for (int m = 0; m < 4; ++m)
; #pragma unroll
;                     for (int n = 0; n < 2; ++n) acc[a][b][m][n] = (f32x4){0.f, 0.f, 0.f, 0.f};
;         cur = nxt; cA = nA; cB = nB; ++ui;
;         if constexpr (ALIGN_EPI) { if (wr == 1) PG8_BAR; }
;     }
	v_sub_f32_e32 v201, v201, v194
	v_sub_f32_e32 v200, v200, v194
	v_sub_f32_e32 v199, v199, v194
	v_sub_f32_e32 v198, v198, v194
	v_pk_mul_f32 v[198:199], v[194:195], v[198:199] op_sel:[1,0]
	v_pk_mul_f32 v[200:201], v[194:195], v[200:201] op_sel:[1,0]
	v_pk_fma_f32 v[198:199], v[144:145], v[198:199], v[174:175]
	v_pk_fma_f32 v[200:201], v[146:147], v[200:201], v[176:177]
	v_pk_add_f32 v[20:21], v[20:21], v[198:199]
	v_pk_add_f32 v[22:23], v[22:23], v[200:201]
	s_nop 0
	v_cvt_pk_f16_f32 v23, v22, v23
	v_cvt_pk_f16_f32 v22, v20, v21
	global_store_dwordx2 v247, v[22:23], s[46:47] offset:256
	s_waitcnt vmcnt(16)
	v_sub_f32_e32 v205, v205, v194
	v_sub_f32_e32 v204, v204, v194
	v_sub_f32_e32 v203, v203, v194
	v_sub_f32_e32 v202, v202, v194
	v_pk_mul_f32 v[202:203], v[194:195], v[202:203] op_sel:[1,0]
	v_pk_mul_f32 v[204:205], v[194:195], v[204:205] op_sel:[1,0]
	v_pk_fma_f32 v[202:203], v[148:149], v[202:203], v[178:179]
	v_pk_fma_f32 v[204:205], v[150:151], v[204:205], v[180:181]
	v_pk_add_f32 v[16:17], v[16:17], v[202:203]
	v_pk_add_f32 v[18:19], v[18:19], v[204:205]
	s_nop 0
	v_cvt_pk_f16_f32 v19, v18, v19
	v_cvt_pk_f16_f32 v18, v16, v17
	global_store_dwordx2 v247, v[18:19], s[46:47] offset:288
	s_waitcnt vmcnt(15)
	v_sub_f32_e32 v209, v209, v196
	v_sub_f32_e32 v208, v208, v196
	v_sub_f32_e32 v207, v207, v196
	v_sub_f32_e32 v206, v206, v196
	v_pk_mul_f32 v[206:207], v[196:197], v[206:207] op_sel:[1,0]
	v_pk_mul_f32 v[208:209], v[196:197], v[208:209] op_sel:[1,0]
	v_pk_fma_f32 v[206:207], v[136:137], v[206:207], v[166:167]
	v_pk_fma_f32 v[208:209], v[138:139], v[208:209], v[168:169]
	v_pk_add_f32 v[12:13], v[12:13], v[206:207]
	v_pk_add_f32 v[14:15], v[14:15], v[208:209]
	v_add_u32_e32 v247, 0xb0000, v159
	v_lshlrev_b32_e32 v247, 1, v247
	v_cvt_pk_f16_f32 v15, v14, v15
	v_cvt_pk_f16_f32 v14, v12, v13
	global_store_dwordx2 v247, v[14:15], s[46:47]
	s_waitcnt vmcnt(14)
	v_sub_f32_e32 v213, v213, v196
	v_sub_f32_e32 v212, v212, v196
	v_sub_f32_e32 v211, v211, v196
	v_sub_f32_e32 v210, v210, v196
	v_pk_mul_f32 v[210:211], v[196:197], v[210:211] op_sel:[1,0]
	v_pk_mul_f32 v[212:213], v[196:197], v[212:213] op_sel:[1,0]
	v_pk_fma_f32 v[210:211], v[140:141], v[210:211], v[170:171]
	v_pk_fma_f32 v[212:213], v[142:143], v[212:213], v[172:173]
	v_pk_add_f32 v[8:9], v[8:9], v[210:211]
	v_pk_add_f32 v[10:11], v[10:11], v[212:213]
	s_nop 0
	v_cvt_pk_f16_f32 v11, v10, v11
	v_cvt_pk_f16_f32 v10, v8, v9
	global_store_dwordx2 v247, v[10:11], s[46:47] offset:32
	s_waitcnt vmcnt(13)
	v_sub_f32_e32 v217, v217, v196
	v_sub_f32_e32 v216, v216, v196
	v_sub_f32_e32 v215, v215, v196
	v_sub_f32_e32 v214, v214, v196
	v_pk_mul_f32 v[214:215], v[196:197], v[214:215] op_sel:[1,0]
	v_pk_mul_f32 v[216:217], v[196:197], v[216:217] op_sel:[1,0]
	v_pk_fma_f32 v[214:215], v[144:145], v[214:215], v[174:175]
	v_pk_fma_f32 v[216:217], v[146:147], v[216:217], v[176:177]
	v_pk_add_f32 v[4:5], v[4:5], v[214:215]
	v_pk_add_f32 v[6:7], v[6:7], v[216:217]
	s_nop 0
	v_cvt_pk_f16_f32 v7, v6, v7
	v_cvt_pk_f16_f32 v6, v4, v5
	global_store_dwordx2 v247, v[6:7], s[46:47] offset:256
	s_waitcnt vmcnt(12)
	v_sub_f32_e32 v221, v221, v196
	v_sub_f32_e32 v220, v220, v196
	v_sub_f32_e32 v219, v219, v196
	v_sub_f32_e32 v218, v218, v196
	v_pk_mul_f32 v[218:219], v[196:197], v[218:219] op_sel:[1,0]
	v_pk_mul_f32 v[220:221], v[196:197], v[220:221] op_sel:[1,0]
	v_pk_fma_f32 v[218:219], v[148:149], v[218:219], v[178:179]
	v_pk_fma_f32 v[220:221], v[150:151], v[220:221], v[180:181]
	v_pk_add_f32 v[0:1], v[0:1], v[218:219]
	v_pk_add_f32 v[2:3], v[2:3], v[220:221]
	s_nop 0
	v_cvt_pk_f16_f32 v3, v2, v3
	v_cvt_pk_f16_f32 v2, v0, v1
	global_store_dwordx2 v247, v[2:3], s[46:47] offset:288
	s_cbranch_vccnz .LBB0_806
	s_andn2_b64 vcc, exec, s[12:13]
	s_cbranch_vccnz .LBB0_805
	s_barrier
	s_branch .LBB0_805
